# v8: gla_pass3 items redistributed across workgroups inversely to their MLA attention item length (static bijective remap); plus earlier W1/epilogue/tile-load edits
# speedup vs baseline: 1.0478x; 1.0102x over previous
; DI unsigned pack2(float lo, float hi) { unsigned r; asm("v_cvt_pk_bf16_f32 %0, %1, %2" : "=v"(r) : "v"(lo), "v"(hi)); return r; }
; DI void load_tile_v(int tid, const bf16_t* __restrict__ g, int ld, char* dst) { u32x4 r[4]; ldg_tile(tid, g, ld, r); sts_tile_v(tid, r, dst); }
; DI void gla_pass3(int item, const bf16_t* __restrict__ z, const float* __restrict__ w_up, const float* __restrict__ b_alpha,
;                   const float* __restrict__ Sbuf, const float* __restrict__ gw, bf16_t* __restrict__ mix, char* smem) {
;     ...
; #pragma unroll
;     for (int kt = 0; kt < 4; ++kt)
; #pragma unroll
;       for (int r = 0; r < 4; ++r) sq[kt][0][r] = qdT[(kt * 16 + 4 * g + r) * 68 + iq];
;     __syncthreads();
; #pragma unroll
;     for (int i = 0; i < 4; ++i) {
;       f32x4 o;
; #pragma unroll
;       for (int j = 0; j < 4; ++j) o[j] = (tj * 4 + j <= ti * 4 + i) ? a4[i][j] : 0.f;
;       *(f32x4*)(kiT + (ti * 4 + i) * 68 + tj * 4) = o;
;     }
;   }
;   load_tile_v(tid, z + tok0 * ABP + ZV + h * 128, ABP, Vs);
;   {
;     const float* Sg = Sbuf + (size_t)item * 64 * 128;
; #pragma unroll
;     for (int i = 0; i < 4; ++i) {
;       const int idx = tid + 256 * i, row = idx >> 4, ch = idx & 15;
;       const f32x4 x0 = *(const f32x4*)(Sg + row * 128 + ch * 8), x1 = *(const f32x4*)(Sg + row * 128 + ch * 8 + 4);
;       u32x4 w; w[0] = pack2(x0[0], x0[1]); w[1] = pack2(x0[2], x0[3]); w[2] = pack2(x1[0], x1[1]); w[3] = pack2(x1[2], x1[3]);
;       *(u32x4*)(Ss + voff(row, ch)) = w;
; __global__ void __launch_bounds__(256, 2) mega(Params p) {
;     ...
;       for (int it = blockIdx.x; it < 1024; it += gridDim.x) gla_pass3(it, zb, p.in[8] + (size_t)j * 16 * 512, p.in[9] + (size_t)j * 512, Ubuf, p.in[10] + j * 128, mix, smem);
.LBB0_950:
	s_or_b64 exec, exec, s[0:1]
	v_readlane_b32 s0, v251, 1
	v_readlane_b32 s1, v251, 2
	s_and_b64 vcc, exec, s[0:1]
	s_movk_i32 s4, 0x2100
	s_waitcnt lgkmcnt(0)
	s_barrier
	s_cbranch_vccz .LBB0_960
	v_readlane_b32 s2, v254, 44
	v_readlane_b32 s3, v254, 45
	s_lshl_b64 s[0:1], s[2:3], 15
	v_readlane_b32 s8, v250, 18
	v_readlane_b32 s9, v250, 19
	s_add_u32 s6, s8, s0
	v_readlane_b32 s10, v250, 20
	s_addc_u32 s7, s9, s1
	s_lshl_b64 s[0:1], s[2:3], 11
	v_readlane_b32 s11, v250, 21
	s_add_u32 s8, s10, s0
	s_addc_u32 s9, s11, s1
	s_mov_b32 s1, s97
	s_lshl_b32 s0, s2, 7
	v_readlane_b32 s12, v250, 22
	s_lshl_b64 s[0:1], s[0:1], 2
	v_readlane_b32 s13, v250, 23
	s_add_u32 s10, s12, s0
	s_addc_u32 s11, s13, s1
	s_lshr_b32 s100, s82, 5
	s_add_i32 s100, s100, 2
	s_lshr_b32 s101, s100, 2
	s_and_b32 s100, s100, 3
	s_mul_i32 s100, s101, s100
	s_add_i32 s12, s101, -1
	s_mul_i32 s12, s12, s101
	s_lshl_b32 s12, s12, 1
	s_add_i32 s12, s12, s100
	s_lshl_b32 s12, s12, 5
	s_and_b32 s100, s82, 31
	s_add_i32 s12, s12, s100
	s_lshl_b32 s101, s101, 5
	s_add_i32 s101, s12, s101
	v_readlane_b32 s14, v250, 24
	v_readlane_b32 s15, v250, 25
	v_readlane_b32 s16, v250, 26
	v_readlane_b32 s17, v250, 27
	v_readlane_b32 s18, v250, 28
	v_readlane_b32 s19, v250, 29
	v_readlane_b32 s20, v250, 30
	v_readlane_b32 s21, v250, 31
	v_readlane_b32 s22, v250, 32
	v_readlane_b32 s23, v250, 33
	s_cmp_ge_i32 s12, s101
	s_cbranch_scc1 .LBB0_960
	s_branch .LBB0_953
.LBB0_952:
	s_or_b64 exec, exec, s[0:1]
	v_lshrrev_b32_e32 v0, 2, v40
	v_and_b32_e32 v41, 12, v0
	v_and_or_b32 v38, v8, -16, v9
	v_mul_u32_u24_e32 v0, 0x110, v41
	v_lshl_add_u32 v0, v38, 2, v0
	v_add_u32_e32 v8, 0x1000, v0
	ds_read2_b32 v[22:23], v0 offset1:68
	ds_read2_b32 v[24:25], v0 offset0:136 offset1:204
	ds_read2_b32 v[26:27], v8 offset0:64 offset1:132
	v_add_u32_e32 v8, 0x1200, v0
	ds_read2_b32 v[28:29], v8 offset0:72 offset1:140
	v_add_u32_e32 v8, 0x2000, v0
	ds_read2_b32 v[14:15], v8 offset0:128 offset1:196
	v_add_u32_e32 v8, 0x2400, v0
	ds_read2_b32 v[16:17], v8 offset0:8 offset1:76
	v_add_u32_e32 v8, 0x3200, v0
	v_add_u32_e32 v0, 0x3400, v0
	ds_read2_b32 v[18:19], v8 offset0:64 offset1:132
	ds_read2_b32 v[20:21], v0 offset0:72 offset1:140
	v_lshlrev_b32_e32 v0, 2, v9
	v_lshlrev_b32_e32 v8, 2, v3
	v_cmp_lt_i32_e64 s[0:1], v0, v8
	v_or_b32_e32 v48, 3, v0
	v_cmp_gt_i32_e32 vcc, v0, v8
	v_cndmask_b32_e64 v43, 0, v37, s[0:1]
	v_cndmask_b32_e64 v44, 0, v34, s[0:1]
	v_cmp_le_i32_e64 s[0:1], v48, v8
	v_cndmask_b32_e64 v42, v36, 0, vcc
	v_or_b32_e32 v36, 1, v8
	v_cndmask_b32_e64 v45, 0, v35, s[0:1]
	s_movk_i32 s0, 0x440
	v_mad_u64_u32 v[34:35], s[0:1], v3, s0, v[2:3]
	v_or_b32_e32 v47, 2, v0
	v_cmp_le_i32_e64 s[0:1], v0, v36
	s_waitcnt lgkmcnt(0)
	s_barrier
	v_cndmask_b32_e64 v32, 0, v32, s[0:1]
	v_cmp_le_i32_e64 s[0:1], v47, v36
	ds_write_b128 v34, v[42:45] offset:17408
	s_nop 0
	v_cndmask_b32_e64 v34, 0, v30, s[0:1]
	v_cmp_le_i32_e64 s[0:1], v48, v36
	s_movk_i32 s5, 0x110
	v_cndmask_b32_e64 v33, v33, 0, vcc
	v_cndmask_b32_e64 v35, 0, v31, s[0:1]
	v_mad_u64_u32 v[36:37], s[0:1], v36, s5, v[2:3]
	ds_write_b128 v36, v[32:35] offset:17408
	v_or_b32_e32 v33, 2, v8
	v_cmp_le_i32_e64 s[0:1], v0, v33
	v_or_b32_e32 v8, 3, v8
	v_cndmask_b32_e64 v32, v10, 0, vcc
	v_cndmask_b32_e64 v30, 0, v12, s[0:1]
	v_cmp_le_i32_e64 s[0:1], v48, v33
	s_movk_i32 s4, 0x2100
	v_cndmask_b32_e64 v31, v13, 0, vcc
	v_cndmask_b32_e64 v33, 0, v11, s[0:1]
	v_cmp_le_i32_e64 s[0:1], v0, v8
	v_cndmask_b32_e64 v13, v5, 0, vcc
	ds_write_b128 v36, v[30:33] offset:17680
	v_cndmask_b32_e64 v10, 0, v6, s[0:1]
	v_cmp_lt_i32_e64 s[0:1], v0, v8
	v_lshlrev_b32_e32 v0, 4, v40
	v_and_b32_e32 v0, 0xf0, v0
	v_cndmask_b32_e64 v11, 0, v7, s[0:1]
	v_cmp_le_i32_e64 s[0:1], v47, v8
	v_lshrrev_b32_e32 v46, 4, v40
	v_and_b32_e32 v2, 16, v2
	v_cndmask_b32_e64 v12, 0, v4, s[0:1]
	s_mul_i32 s0, s15, 0x2100
	s_mul_hi_u32 s1, s14, 0x2100
	s_add_i32 s1, s1, s0
	s_mul_i32 s0, s14, 0x2100
	s_add_u32 s2, s86, s0
	s_addc_u32 s1, s87, s1
	s_lshl_b32 s0, s13, 8
	s_add_u32 s2, s2, s0
	s_addc_u32 s3, s1, 0
	v_lshl_add_u64 v[34:35], s[2:3], 0, v[0:1]
	v_mad_i64_i32 v[4:5], s[2:3], v3, s4, v[34:35]
	global_load_dwordx4 v[4:7], v[4:5], off offset:2048
	v_add_u32_e32 v0, 0x100, v40
	v_ashrrev_i32_e32 v42, 4, v0
	ds_write_b128 v36, v[10:13] offset:17952
	v_mad_i64_i32 v[10:11], s[2:3], v42, s4, v[34:35]
	v_add_u32_e32 v0, 0x200, v40
	global_load_dwordx4 v[10:13], v[10:11], off offset:2048
	v_ashrrev_i32_e32 v43, 4, v0
	v_add_u32_e32 v0, 0x300, v40
	v_ashrrev_i32_e32 v44, 4, v0
	v_mad_i64_i32 v[30:31], s[2:3], v43, s4, v[34:35]
	v_mad_i64_i32 v[34:35], s[2:3], v44, s4, v[34:35]
	global_load_dwordx4 v[30:33], v[30:31], off offset:2048
	v_lshrrev_b32_e32 v0, 1, v9
	global_load_dwordx4 v[34:37], v[34:35], off offset:2048
	v_bitop3_b32 v45, v46, v0, 7 bitop3:0x6c
	v_lshlrev_b32_e32 v8, 8, v3
	v_lshlrev_b32_e32 v45, 5, v45
	v_or3_b32 v45, v45, v8, v2
	s_ashr_i32 s13, s12, 31
	s_lshl_b64 s[2:3], s[12:13], 15
	s_add_u32 s2, s84, s2
	s_addc_u32 s3, s85, s3
	s_mov_b32 s1, 0x800000
	s_waitcnt vmcnt(3)
	ds_write_b128 v45, v[4:7]
	v_bitop3_b32 v5, v42, v0, 7 bitop3:0x6c
	v_lshlrev_b32_e32 v4, 8, v42
	v_lshlrev_b32_e32 v5, 5, v5
	v_or3_b32 v46, v5, v4, v2
	v_bitop3_b32 v5, v43, v0, 7 bitop3:0x6c
	v_lshlrev_b32_e32 v4, 8, v43
	v_lshlrev_b32_e32 v5, 5, v5
	v_bitop3_b32 v0, v44, v0, 7 bitop3:0x6c
	s_waitcnt vmcnt(2)
	ds_write_b128 v46, v[10:13]
	v_or3_b32 v12, v5, v4, v2
	v_lshlrev_b32_e32 v4, 8, v44
	v_lshlrev_b32_e32 v0, 5, v0
	v_or3_b32 v13, v0, v4, v2
	v_lshlrev_b32_e32 v0, 5, v9
	v_lshlrev_b32_e32 v2, 7, v3
	v_lshl_add_u64 v[10:11], s[2:3], 0, v[0:1]
	v_ashrrev_i32_e32 v3, 31, v2
	s_waitcnt vmcnt(1)
; template <int QS>
; DI void pv_tile(const char* Vs, const f32x4 (&s)[4][QS], f32x4 (&o)[QS][8], int lane) {
;   const int g = lane >> 4, i = lane & 15;
; #pragma unroll
;   for (int c = 0; c < 2; ++c) {
;     bf16x8 pf[QS];
; #pragma unroll
;     for (int qs = 0; qs < QS; ++qs) {
;       union { uint4 u; bf16x8 v; } cv;
;       cv.u.x = pack2(s[2 * c][qs][0], s[2 * c][qs][1]); cv.u.y = pack2(s[2 * c][qs][2], s[2 * c][qs][3]);
;       cv.u.z = pack2(s[2 * c + 1][qs][0], s[2 * c + 1][qs][1]); cv.u.w = pack2(s[2 * c + 1][qs][2], s[2 * c + 1][qs][3]);
;       pf[qs] = cv.v;
;     }
;     const int r1 = 32 * c + 4 * g + (i >> 2), r2 = r1 + 16;
; #pragma unroll
;     for (int dt = 0; dt < 8; ++dt) {
;       const s16x4 lo = __builtin_amdgcn_ds_read_tr16_b64_v4i16(LDSP(s16x4, Vs + r1 * 256 + ((dt ^ (r1 & 7)) << 5) + 8 * (i & 3)));
;       const s16x4 hi = __builtin_amdgcn_ds_read_tr16_b64_v4i16(LDSP(s16x4, Vs + r2 * 256 + ((dt ^ (r2 & 7)) << 5) + 8 * (i & 3)));
;       bf16x8 vf; vf[0] = lo[0]; vf[1] = lo[1]; vf[2] = lo[2]; vf[3] = lo[3]; vf[4] = hi[0]; vf[5] = hi[1]; vf[6] = hi[2]; vf[7] = hi[3];
; #pragma unroll
;       for (int qs = 0; qs < QS; ++qs) o[qs][dt] = __builtin_amdgcn_mfma_f32_16x16x32_bf16(vf, pf[qs], o[qs][dt], 0, 0, 0);
; DI void gla_pass3(int item, const bf16_t* __restrict__ z, const float* __restrict__ w_up, const float* __restrict__ b_alpha,
;                   const float* __restrict__ Sbuf, const float* __restrict__ gw, bf16_t* __restrict__ mix, char* smem) {
;     ...
;   load_tile_v(tid, z + tok0 * ABP + ZV + h * 128, ABP, Vs);
;   {
;     const float* Sg = Sbuf + (size_t)item * 64 * 128;
; #pragma unroll
;     for (int i = 0; i < 4; ++i) {
;       const int idx = tid + 256 * i, row = idx >> 4, ch = idx & 15;
;       const f32x4 x0 = *(const f32x4*)(Sg + row * 128 + ch * 8), x1 = *(const f32x4*)(Sg + row * 128 + ch * 8 + 4);
;       u32x4 w; w[0] = pack2(x0[0], x0[1]); w[1] = pack2(x0[2], x0[3]); w[2] = pack2(x1[0], x1[1]); w[3] = pack2(x1[2], x1[3]);
;       *(u32x4*)(Ss + voff(row, ch)) = w;
;     }
;   }
;   __syncthreads();
;   f32x4 o[1][8];
; #pragma unroll
;   for (int dt = 0; dt < 8; ++dt) o[0][dt] = (f32x4){0.f, 0.f, 0.f, 0.f};
;   {
;     f32x4 sa[4][1];
; #pragma unroll
;     for (int kt = 0; kt < 4; ++kt) sa[kt][0] = *(const f32x4*)(kiT + iq * 68 + kt * 16 + 4 * g);
;     pv_tile<1>(Vs, sa, o, lane);
;     pv_tile<1>(Ss, sq, o, lane);
	ds_write_b128 v12, v[30:33]
	s_waitcnt vmcnt(0)
	ds_write_b128 v13, v[34:37]
	v_lshl_add_u64 v[6:7], v[2:3], 2, v[10:11]
	global_load_dwordx4 v[2:5], v[6:7], off offset:16
	s_nop 0
	global_load_dwordx4 v[6:9], v[6:7], off
	v_and_b32_e32 v0, 48, v40
	v_lshlrev_b32_e32 v31, 3, v39
	v_cvt_pk_bf16_f32 v36, v18, v19
	v_cvt_pk_bf16_f32 v37, v20, v21
	s_waitcnt vmcnt(0)
	v_cvt_pk_bf16_f32 v6, v6, v7
	v_cvt_pk_bf16_f32 v7, v8, v9
	v_cvt_pk_bf16_f32 v8, v2, v3
	v_lshlrev_b32_e32 v2, 7, v42
	v_ashrrev_i32_e32 v3, 31, v2
	v_cvt_pk_bf16_f32 v9, v4, v5
	ds_write_b128 v45, v[6:9] offset:34816
	v_lshl_add_u64 v[6:7], v[2:3], 2, v[10:11]
	global_load_dwordx4 v[2:5], v[6:7], off offset:16
	s_nop 0
	global_load_dwordx4 v[6:9], v[6:7], off
	s_waitcnt vmcnt(0)
	v_cvt_pk_bf16_f32 v6, v6, v7
	v_cvt_pk_bf16_f32 v7, v8, v9
	v_cvt_pk_bf16_f32 v8, v2, v3
	v_lshlrev_b32_e32 v2, 7, v43
	v_ashrrev_i32_e32 v3, 31, v2
	v_cvt_pk_bf16_f32 v9, v4, v5
	ds_write_b128 v46, v[6:9] offset:34816
	v_lshl_add_u64 v[6:7], v[2:3], 2, v[10:11]
	global_load_dwordx4 v[2:5], v[6:7], off offset:16
	s_nop 0
	global_load_dwordx4 v[6:9], v[6:7], off
	s_waitcnt vmcnt(0)
	v_cvt_pk_bf16_f32 v6, v6, v7
	v_cvt_pk_bf16_f32 v7, v8, v9
	v_cvt_pk_bf16_f32 v8, v2, v3
	v_lshlrev_b32_e32 v2, 7, v44
	v_ashrrev_i32_e32 v3, 31, v2
	v_cvt_pk_bf16_f32 v9, v4, v5
	ds_write_b128 v12, v[6:9] offset:34816
	v_lshl_add_u64 v[6:7], v[2:3], 2, v[10:11]
	global_load_dwordx4 v[2:5], v[6:7], off offset:16
	s_nop 0
	global_load_dwordx4 v[6:9], v[6:7], off
	v_mad_u64_u32 v[10:11], s[2:3], v38, s5, v[0:1]
	s_waitcnt vmcnt(0)
	v_cvt_pk_bf16_f32 v6, v6, v7
	v_cvt_pk_bf16_f32 v7, v8, v9
	v_cvt_pk_bf16_f32 v8, v2, v3
	v_cvt_pk_bf16_f32 v9, v4, v5
	v_lshlrev_b32_e32 v0, 6, v39
	ds_write_b128 v13, v[6:9] offset:34816
	s_waitcnt lgkmcnt(0)
	s_barrier
	ds_read_b128 v[2:5], v10 offset:17408
	ds_read_b128 v[6:9], v10 offset:17472
	ds_read_b128 v[32:35], v10 offset:17536
	ds_read_b128 v[46:49], v10 offset:17600
	v_and_b32_e32 v0, 0xf00, v0
	v_and_b32_e32 v10, 0xe0, v31
	v_and_or_b32 v0, v31, 24, v0
	v_or_b32_e32 v30, v0, v10
	s_waitcnt lgkmcnt(3)
	v_cvt_pk_bf16_f32 v2, v2, v3
	v_cvt_pk_bf16_f32 v3, v4, v5
	s_waitcnt lgkmcnt(2)
	v_cvt_pk_bf16_f32 v4, v6, v7
	v_cvt_pk_bf16_f32 v5, v8, v9
	ds_read_b64_tr_b16 v[6:7], v30
	ds_read_b64_tr_b16 v[8:9], v30 offset:4096
	s_waitcnt lgkmcnt(0)
	v_mfma_f32_16x16x32_bf16 v[50:53], v[6:9], v[2:5], 0
	v_bitop3_b32 v6, v31, 32, v200 bitop3:0x6c
	v_or_b32_e32 v45, v0, v6
	ds_read_b64_tr_b16 v[6:7], v45
	ds_read_b64_tr_b16 v[8:9], v45 offset:4096
	s_waitcnt lgkmcnt(0)
	v_mfma_f32_16x16x32_bf16 v[54:57], v[6:9], v[2:5], 0
	v_bitop3_b32 v6, v31, 64, v200 bitop3:0x6c
	v_or_b32_e32 v44, v0, v6
	ds_read_b64_tr_b16 v[6:7], v44
	ds_read_b64_tr_b16 v[8:9], v44 offset:4096
	s_waitcnt lgkmcnt(0)
	v_mfma_f32_16x16x32_bf16 v[58:61], v[6:9], v[2:5], 0
	v_bitop3_b32 v6, v31, s92, v200 bitop3:0x6c
	v_or_b32_e32 v43, v0, v6
	ds_read_b64_tr_b16 v[6:7], v43
	ds_read_b64_tr_b16 v[8:9], v43 offset:4096
	s_waitcnt lgkmcnt(0)
	v_mfma_f32_16x16x32_bf16 v[62:65], v[6:9], v[2:5], 0
	v_bitop3_b32 v6, v31, s95, v200 bitop3:0x6c
	v_or_b32_e32 v42, v0, v6
	ds_read_b64_tr_b16 v[6:7], v42
	ds_read_b64_tr_b16 v[8:9], v42 offset:4096
	s_waitcnt lgkmcnt(0)
	v_mfma_f32_16x16x32_bf16 v[66:69], v[6:9], v[2:5], 0
	v_bitop3_b32 v6, v31, s71, v200 bitop3:0x6c
	v_or_b32_e32 v40, v0, v6
	ds_read_b64_tr_b16 v[6:7], v40
	ds_read_b64_tr_b16 v[8:9], v40 offset:4096
	s_waitcnt lgkmcnt(0)
	v_mfma_f32_16x16x32_bf16 v[70:73], v[6:9], v[2:5], 0
	v_bitop3_b32 v6, v31, s68, v200 bitop3:0x6c
	v_or_b32_e32 v39, v0, v6
	ds_read_b64_tr_b16 v[6:7], v39
	ds_read_b64_tr_b16 v[8:9], v39 offset:4096
	s_waitcnt lgkmcnt(0)
	v_mfma_f32_16x16x32_bf16 v[10:13], v[6:9], v[2:5], 0
	v_bitop3_b32 v6, v31, s69, v31 bitop3:0xc
	v_or_b32_e32 v0, v0, v6
	ds_read_b64_tr_b16 v[6:7], v0
	ds_read_b64_tr_b16 v[8:9], v0 offset:4096
	s_waitcnt lgkmcnt(0)
	v_mfma_f32_16x16x32_bf16 v[2:5], v[6:9], v[2:5], 0
	v_cvt_pk_bf16_f32 v6, v32, v33
	v_cvt_pk_bf16_f32 v7, v34, v35
	ds_read_b64_tr_b16 v[32:33], v30 offset:8192
	ds_read_b64_tr_b16 v[34:35], v30 offset:12288
	v_cvt_pk_bf16_f32 v8, v46, v47
	v_cvt_pk_bf16_f32 v9, v48, v49
	ds_read_b64_tr_b16 v[46:47], v45 offset:8192
	ds_read_b64_tr_b16 v[48:49], v45 offset:12288
	s_waitcnt lgkmcnt(2)
	v_mfma_f32_16x16x32_bf16 v[32:35], v[32:35], v[6:9], v[50:53]
	s_nop 2
	ds_read_b64_tr_b16 v[50:51], v44 offset:8192
	ds_read_b64_tr_b16 v[52:53], v44 offset:12288
	s_waitcnt lgkmcnt(2)
	v_mfma_f32_16x16x32_bf16 v[46:49], v[46:49], v[6:9], v[54:57]
	s_nop 2
	ds_read_b64_tr_b16 v[54:55], v43 offset:8192
	ds_read_b64_tr_b16 v[56:57], v43 offset:12288
	s_waitcnt lgkmcnt(2)
	v_mfma_f32_16x16x32_bf16 v[50:53], v[50:53], v[6:9], v[58:61]
	s_nop 2
	ds_read_b64_tr_b16 v[58:59], v42 offset:8192
	ds_read_b64_tr_b16 v[60:61], v42 offset:12288
	s_waitcnt lgkmcnt(2)
	v_mfma_f32_16x16x32_bf16 v[54:57], v[54:57], v[6:9], v[62:65]
	s_nop 2
	ds_read_b64_tr_b16 v[62:63], v40 offset:8192
	ds_read_b64_tr_b16 v[64:65], v40 offset:12288
	s_waitcnt lgkmcnt(2)
	v_mfma_f32_16x16x32_bf16 v[58:61], v[58:61], v[6:9], v[66:69]
	s_nop 2
	ds_read_b64_tr_b16 v[66:67], v39 offset:8192
	ds_read_b64_tr_b16 v[68:69], v39 offset:12288
	s_waitcnt lgkmcnt(0)
	v_mfma_f32_16x16x32_bf16 v[10:13], v[66:69], v[6:9], v[10:13]
	ds_read_b64_tr_b16 v[66:67], v0 offset:8192
	ds_read_b64_tr_b16 v[68:69], v0 offset:12288
	v_mfma_f32_16x16x32_bf16 v[62:65], v[62:65], v[6:9], v[70:73]
	s_waitcnt lgkmcnt(0)
; DI void gla_pass3(int item, const bf16_t* __restrict__ z, const float* __restrict__ w_up, const float* __restrict__ b_alpha,
;                   const float* __restrict__ Sbuf, const float* __restrict__ gw, bf16_t* __restrict__ mix, char* smem) {
;     ...
;     pv_tile<1>(Vs, sa, o, lane);
;     pv_tile<1>(Ss, sq, o, lane);
;   }
;   {
;     float ssq = 0.f;
; #pragma unroll
;     for (int dt = 0; dt < 8; ++dt) ssq += (o[0][dt][0] * o[0][dt][0] + o[0][dt][1] * o[0][dt][1]) + (o[0][dt][2] * o[0][dt][2] + o[0][dt][3] * o[0][dt][3]);
;     ssq += __shfl_xor(ssq, 16); ssq += __shfl_xor(ssq, 32);
	v_mfma_f32_16x16x32_bf16 v[2:5], v[66:69], v[6:9], v[2:5]
	v_cvt_pk_bf16_f32 v6, v22, v23
	v_cvt_pk_bf16_f32 v7, v24, v25
	ds_read_b64_tr_b16 v[22:23], v30 offset:34816
	ds_read_b64_tr_b16 v[24:25], v30 offset:38912
	v_cvt_pk_bf16_f32 v8, v26, v27
	v_cvt_pk_bf16_f32 v9, v28, v29
	ds_read_b64_tr_b16 v[26:27], v45 offset:34816
	ds_read_b64_tr_b16 v[28:29], v45 offset:38912
	s_waitcnt lgkmcnt(2)
	v_mfma_f32_16x16x32_bf16 v[22:25], v[22:25], v[6:9], v[32:35]
	s_nop 2
	ds_read_b64_tr_b16 v[32:33], v44 offset:34816
	ds_read_b64_tr_b16 v[34:35], v44 offset:38912
	s_waitcnt lgkmcnt(2)
	v_mfma_f32_16x16x32_bf16 v[26:29], v[26:29], v[6:9], v[46:49]
	s_waitcnt lgkmcnt(0)
	v_mfma_f32_16x16x32_bf16 v[46:49], v[32:35], v[6:9], v[50:53]
	ds_read_b64_tr_b16 v[32:33], v43 offset:34816
	ds_read_b64_tr_b16 v[34:35], v43 offset:38912
	s_waitcnt lgkmcnt(0)
	v_mfma_f32_16x16x32_bf16 v[50:53], v[32:35], v[6:9], v[54:57]
	ds_read_b64_tr_b16 v[32:33], v42 offset:34816
	ds_read_b64_tr_b16 v[34:35], v42 offset:38912
	s_waitcnt lgkmcnt(0)
	v_mfma_f32_16x16x32_bf16 v[54:57], v[32:35], v[6:9], v[58:61]
	ds_read_b64_tr_b16 v[32:33], v40 offset:34816
	ds_read_b64_tr_b16 v[34:35], v40 offset:38912
	s_waitcnt lgkmcnt(0)
	v_mfma_f32_16x16x32_bf16 v[58:61], v[32:35], v[6:9], v[62:65]
	ds_read_b64_tr_b16 v[32:33], v39 offset:34816
	ds_read_b64_tr_b16 v[34:35], v39 offset:38912
	s_waitcnt lgkmcnt(0)
	v_mfma_f32_16x16x32_bf16 v[62:65], v[32:35], v[6:9], v[10:13]
	s_nop 2
	ds_read_b64_tr_b16 v[10:11], v0 offset:34816
	ds_read_b64_tr_b16 v[12:13], v0 offset:38912
	v_cvt_pk_bf16_f32 v34, v14, v15
	v_cvt_pk_bf16_f32 v35, v16, v17
	s_waitcnt lgkmcnt(0)
	v_mfma_f32_16x16x32_bf16 v[2:5], v[10:13], v[6:9], v[2:5]
	ds_read_b64_tr_b16 v[6:7], v30 offset:43008
	ds_read_b64_tr_b16 v[8:9], v30 offset:47104
	s_waitcnt lgkmcnt(0)
	v_mfma_f32_16x16x32_bf16 v[30:33], v[6:9], v[34:37], v[22:25]
	ds_read_b64_tr_b16 v[6:7], v45 offset:43008
	ds_read_b64_tr_b16 v[8:9], v45 offset:47104
	s_waitcnt lgkmcnt(0)
	v_mfma_f32_16x16x32_bf16 v[26:29], v[6:9], v[34:37], v[26:29]
	ds_read_b64_tr_b16 v[6:7], v44 offset:43008
	ds_read_b64_tr_b16 v[8:9], v44 offset:47104
	s_waitcnt lgkmcnt(0)
	v_mfma_f32_16x16x32_bf16 v[22:25], v[6:9], v[34:37], v[46:49]
	ds_read_b64_tr_b16 v[6:7], v43 offset:43008
	ds_read_b64_tr_b16 v[8:9], v43 offset:47104
	s_waitcnt lgkmcnt(0)
	v_mfma_f32_16x16x32_bf16 v[18:21], v[6:9], v[34:37], v[50:53]
	ds_read_b64_tr_b16 v[6:7], v42 offset:43008
	ds_read_b64_tr_b16 v[8:9], v42 offset:47104
	s_waitcnt lgkmcnt(0)
	v_mfma_f32_16x16x32_bf16 v[14:17], v[6:9], v[34:37], v[54:57]
	ds_read_b64_tr_b16 v[6:7], v40 offset:43008
	ds_read_b64_tr_b16 v[8:9], v40 offset:47104
	s_waitcnt lgkmcnt(0)
	v_mfma_f32_16x16x32_bf16 v[10:13], v[6:9], v[34:37], v[58:61]
	ds_read_b64_tr_b16 v[6:7], v39 offset:43008
	ds_read_b64_tr_b16 v[8:9], v39 offset:47104
	ds_read_b64_tr_b16 v[42:43], v0 offset:43008
	ds_read_b64_tr_b16 v[44:45], v0 offset:47104
	v_mul_f32_e32 v0, v14, v14
	s_waitcnt lgkmcnt(2)
	v_mfma_f32_16x16x32_bf16 v[6:9], v[6:9], v[34:37], v[62:65]
	v_mul_f32_e32 v39, v15, v15
	v_mul_f32_e32 v40, v16, v16
	s_waitcnt lgkmcnt(0)
	v_mfma_f32_16x16x32_bf16 v[2:5], v[42:45], v[34:37], v[2:5]
	v_mov_b32_e32 v36, v31
	v_mov_b32_e32 v37, v27
	v_mov_b32_e32 v34, v30
	v_mov_b32_e32 v35, v26
	v_pk_mul_f32 v[36:37], v[36:37], v[36:37]
	v_mov_b32_e32 v42, v33
	v_mov_b32_e32 v43, v29
	v_pk_fma_f32 v[34:35], v[34:35], v[34:35], v[36:37]
	v_mov_b32_e32 v36, v32
	v_mov_b32_e32 v37, v28
	v_pk_mul_f32 v[42:43], v[42:43], v[42:43]
	s_nop 0
	v_pk_fma_f32 v[36:37], v[36:37], v[36:37], v[42:43]
	v_pk_mul_f32 v[42:43], v[22:23], v[22:23]
	v_pk_add_f32 v[34:35], v[34:35], v[36:37]
	v_pk_mul_f32 v[36:37], v[24:25], v[24:25]
	v_pk_add_f32 v[34:35], v[34:35], v[34:35] op_sel:[0,1] op_sel_hi:[1,0]
	v_pk_mov_b32 v[44:45], v[42:43], v[36:37] op_sel:[1,0]
	v_mov_b32_e32 v43, v37
	v_pk_add_f32 v[36:37], v[44:45], v[42:43]
	v_mov_b32_e32 v35, v0
	v_pk_add_f32 v[36:37], v[36:37], v[36:37] op_sel:[0,1] op_sel_hi:[1,0]
	v_mul_f32_e32 v0, v19, v19
	v_mov_b32_e32 v37, v39
	v_pk_add_f32 v[34:35], v[34:35], v[36:37]
	v_pk_fma_f32 v[36:37], v[18:19], v[18:19], v[0:1] op_sel_hi:[1,1,0]
	v_mul_f32_e32 v0, v21, v21
	v_mul_f32_e32 v44, v17, v17
	v_pk_fma_f32 v[42:43], v[20:21], v[20:21], v[0:1] op_sel_hi:[1,1,0]
	v_mov_b32_e32 v37, v40
	v_mov_b32_e32 v43, v44
	v_pk_add_f32 v[36:37], v[36:37], v[42:43]
	v_pk_mul_f32 v[42:43], v[10:11], v[10:11]
	v_pk_add_f32 v[34:35], v[34:35], v[36:37]
	v_pk_mul_f32 v[36:37], v[12:13], v[12:13]
	v_mul_f32_e32 v0, v2, v2
	v_pk_mov_b32 v[44:45], v[42:43], v[36:37] op_sel:[1,0]
	v_mov_b32_e32 v43, v37
	v_pk_add_f32 v[36:37], v[44:45], v[42:43]
	v_mul_f32_e32 v39, v3, v3
	v_pk_add_f32 v[34:35], v[34:35], v[34:35] op_sel:[0,1] op_sel_hi:[1,0]
	v_pk_add_f32 v[36:37], v[36:37], v[36:37] op_sel:[0,1] op_sel_hi:[1,0]
	v_mov_b32_e32 v35, v0
	v_mov_b32_e32 v37, v39
	v_mul_f32_e32 v0, v7, v7
	v_pk_add_f32 v[34:35], v[34:35], v[36:37]
	v_pk_fma_f32 v[36:37], v[6:7], v[6:7], v[0:1] op_sel_hi:[1,1,0]
	v_mul_f32_e32 v0, v9, v9
	v_mul_f32_e32 v40, v4, v4
	v_mul_f32_e32 v44, v5, v5
	v_pk_fma_f32 v[42:43], v[8:9], v[8:9], v[0:1] op_sel_hi:[1,1,0]
	v_mov_b32_e32 v37, v40
	v_mov_b32_e32 v43, v44
	v_pk_add_f32 v[36:37], v[36:37], v[42:43]
	v_ashrrev_i32_e32 v39, 31, v38
	v_pk_add_f32 v[34:35], v[34:35], v[36:37]
	v_lshl_add_u64 v[36:37], s[14:15], 0, v[38:39]
	v_add_f32_e32 v0, v34, v35
	v_and_b32_e32 v35, 64, v198
	v_xor_b32_e32 v34, 16, v198
	v_add_u32_e32 v35, 64, v35
	v_cmp_lt_i32_e32 vcc, v34, v35
	s_nop 1
	v_cndmask_b32_e32 v34, v198, v34, vcc
	v_lshlrev_b32_e32 v34, 2, v34
	ds_bpermute_b32 v34, v34, v0
	s_waitcnt lgkmcnt(0)
; DI unsigned pack2(float lo, float hi) { unsigned r; asm("v_cvt_pk_bf16_f32 %0, %1, %2" : "=v"(r) : "v"(lo), "v"(hi)); return r; }
; DI float lo2f(unsigned u) { return __uint_as_float(u << 16); }
; DI float hi2f(unsigned u) { return __uint_as_float(u & 0xffff0000u); }
; DI float sigmoidf_(float x) { return 1.f / (1.f + __expf(-x)); }
; DI void gla_pass3(int item, const bf16_t* __restrict__ z, const float* __restrict__ w_up, const float* __restrict__ b_alpha,
;                   const float* __restrict__ Sbuf, const float* __restrict__ gw, bf16_t* __restrict__ mix, char* smem) {
;     ...
;     ssq += __shfl_xor(ssq, 16); ssq += __shfl_xor(ssq, 32);
;     const float r = rsqrtf(ssq * (1.f / 128.f) + 1e-6f);
; #pragma unroll
;     for (int dt = 0; dt < 8; ++dt) {
;       const int dv = dt * 16 + 4 * g, col = h * 128 + dv;
;       const u32x2 gq = *(const u32x2*)(z + (tok0 + iq) * ABP + ZG + col);
;       const float gg[4] = {lo2f(gq[0]), hi2f(gq[0]), lo2f(gq[1]), hi2f(gq[1])};
;       const f32x4 w = *(const f32x4*)(gw + dv);
;       float y[4];
; #pragma unroll
;       for (int e = 0; e < 4; ++e) y[e] = o[0][dt][e] * r * w[e] * (gg[e] * sigmoidf_(gg[e]));
;       u32x2 ov; ov[0] = pack2(y[0], y[1]); ov[1] = pack2(y[2], y[3]);
;       *(u32x2*)(mix + (tok0 + iq) * DM + col) = ov;
;     }
	v_add_f32_e32 v0, v0, v34
	v_xor_b32_e32 v34, 32, v198
	v_cmp_lt_i32_e32 vcc, v34, v35
	s_nop 1
	v_cndmask_b32_e32 v34, v198, v34, vcc
	v_lshlrev_b32_e32 v34, 2, v34
	ds_bpermute_b32 v34, v34, v0
	s_waitcnt lgkmcnt(0)
	v_add_f32_e32 v0, v0, v34
	v_fmamk_f32 v0, v0, 0x3c000000, v191
	v_cmp_gt_f32_e32 vcc, s1, v0
	v_mul_f32_e32 v34, 0x4b800000, v0
	s_nop 0
	v_cndmask_b32_e32 v0, v0, v34, vcc
	v_rsq_f32_e32 v0, v0
	s_nop 0
	v_mul_f32_e32 v34, 0x45800000, v0
	v_cndmask_b32_e32 v40, v0, v34, vcc
	v_mov_b64_e32 v[34:35], s[86:87]
	v_mad_u64_u32 v[34:35], s[2:3], v36, s4, v[34:35]
	v_mov_b32_e32 v0, v35
	v_mad_u64_u32 v[38:39], s[2:3], v37, s4, v[0:1]
	v_mov_b32_e32 v35, v38
	s_mov_b64 s[2:3], 0x1000
	v_lshl_add_u64 v[34:35], v[34:35], 0, s[2:3]
	v_lshl_or_b32 v0, v41, 1, s0
	v_lshl_add_u64 v[38:39], v[34:35], 0, v[0:1]
	global_load_dwordx2 v[38:39], v[38:39], off
	v_mul_f32_e32 v30, v30, v40
	v_mul_f32_e32 v31, v31, v40
	v_mul_f32_e32 v32, v32, v40
	v_readlane_b32 s2, v251, 32
	v_lshlrev_b64 v[36:37], 12, v[36:37]
	v_readlane_b32 s3, v251, 33
	v_mul_f32_e32 v26, v26, v40
	v_mul_f32_e32 v27, v27, v40
	v_lshl_add_u64 v[36:37], s[2:3], 0, v[36:37]
	v_mul_f32_e32 v28, v28, v40
	v_mul_f32_e32 v29, v29, v40
	v_mul_f32_e32 v22, v22, v40
	v_mul_f32_e32 v23, v23, v40
	v_mul_f32_e32 v24, v24, v40
	v_mul_f32_e32 v25, v25, v40
	v_mul_f32_e32 v18, v18, v40
	v_mul_f32_e32 v19, v19, v40
	v_mul_f32_e32 v20, v20, v40
	v_mul_f32_e32 v21, v21, v40
	v_mul_f32_e32 v14, v14, v40
	v_mul_f32_e32 v15, v15, v40
	v_mul_f32_e32 v16, v16, v40
	v_mul_f32_e32 v17, v17, v40
	v_mul_f32_e32 v10, v10, v40
	v_mul_f32_e32 v11, v11, v40
	v_mul_f32_e32 v12, v12, v40
	v_mul_f32_e32 v13, v13, v40
	v_mul_f32_e32 v6, v6, v40
	v_mul_f32_e32 v7, v7, v40
	v_mul_f32_e32 v8, v8, v40
	v_mul_f32_e32 v9, v9, v40
	v_mul_f32_e32 v2, v2, v40
	v_mul_f32_e32 v3, v3, v40
	v_mul_f32_e32 v4, v4, v40
	v_mul_f32_e32 v5, v5, v40
	s_waitcnt vmcnt(0)
	v_lshlrev_b32_e32 v46, 16, v38
	v_and_b32_e32 v47, 0xffff0000, v38
	v_lshlrev_b32_e32 v38, 2, v41
	global_load_dwordx4 v[42:45], v38, s[10:11]
	v_mul_f32_e32 v41, 0xbfb8aa3b, v46
	v_exp_f32_e32 v41, v41
	v_lshlrev_b32_e32 v48, 16, v39
	v_and_b32_e32 v39, 0xffff0000, v39
	v_add_f32_e32 v41, 1.0, v41
	s_waitcnt vmcnt(0)
	v_mul_f32_e32 v30, v42, v30
	v_div_scale_f32 v42, s[0:1], v41, v41, 1.0
	v_rcp_f32_e32 v49, v42
	v_mul_f32_e32 v31, v43, v31
	v_mul_f32_e32 v32, v44, v32
	v_fma_f32 v50, -v42, v49, 1.0
	v_fmac_f32_e32 v49, v50, v49
	v_div_scale_f32 v50, vcc, 1.0, v41, 1.0
	v_mul_f32_e32 v51, v50, v49
	v_fma_f32 v52, -v42, v51, v50
	v_fmac_f32_e32 v51, v52, v49
	v_fma_f32 v42, -v42, v51, v50
	v_div_fmas_f32 v42, v42, v49, v51
	v_div_fixup_f32 v41, v42, v41, 1.0
	v_mul_f32_e32 v41, v41, v46
	v_mul_f32_e32 v30, v41, v30
	v_mul_f32_e32 v41, 0xbfb8aa3b, v47
	v_exp_f32_e32 v41, v41
	s_nop 0
	v_add_f32_e32 v41, 1.0, v41
	v_div_scale_f32 v42, s[0:1], v41, v41, 1.0
	v_rcp_f32_e32 v43, v42
	s_nop 0
	v_fma_f32 v46, -v42, v43, 1.0
	v_fmac_f32_e32 v43, v46, v43
	v_div_scale_f32 v46, vcc, 1.0, v41, 1.0
	v_mul_f32_e32 v49, v46, v43
	v_fma_f32 v50, -v42, v49, v46
	v_fmac_f32_e32 v49, v50, v43
	v_fma_f32 v42, -v42, v49, v46
	v_div_fmas_f32 v42, v42, v43, v49
	v_div_fixup_f32 v41, v42, v41, 1.0
	v_mul_f32_e32 v41, v41, v47
	v_mul_f32_e32 v31, v41, v31
	v_mul_f32_e32 v41, 0xbfb8aa3b, v48
	v_exp_f32_e32 v41, v41
	s_nop 0
	v_add_f32_e32 v41, 1.0, v41
	v_div_scale_f32 v42, s[0:1], v41, v41, 1.0
	v_rcp_f32_e32 v43, v42
	s_nop 0
	v_fma_f32 v44, -v42, v43, 1.0
	v_fmac_f32_e32 v43, v44, v43
	v_div_scale_f32 v44, vcc, 1.0, v41, 1.0
	v_mul_f32_e32 v46, v44, v43
	v_fma_f32 v47, -v42, v46, v44
	v_fmac_f32_e32 v46, v47, v43
	v_fma_f32 v42, -v42, v46, v44
	v_div_fmas_f32 v42, v42, v43, v46
	v_div_fixup_f32 v41, v42, v41, 1.0
	v_mul_f32_e32 v41, v41, v48
	v_mul_f32_e32 v41, v41, v32
	v_mul_f32_e32 v32, v33, v40
	v_mul_f32_e32 v33, 0xbfb8aa3b, v39
	v_exp_f32_e32 v33, v33
	v_mul_f32_e32 v32, v45, v32
	v_add_f32_e32 v33, 1.0, v33
	v_div_scale_f32 v42, s[0:1], v33, v33, 1.0
	v_rcp_f32_e32 v43, v42
	s_nop 0
	v_fma_f32 v44, -v42, v43, 1.0
	v_fmac_f32_e32 v43, v44, v43
	v_div_scale_f32 v44, vcc, 1.0, v33, 1.0
	v_mul_f32_e32 v45, v44, v43
	v_fma_f32 v46, -v42, v45, v44
	v_fmac_f32_e32 v45, v46, v43
	v_fma_f32 v42, -v42, v45, v44
	v_div_fmas_f32 v42, v42, v43, v45
	v_div_fixup_f32 v33, v42, v33, 1.0
	v_mul_f32_e32 v33, v33, v39
	v_mul_f32_e32 v33, v33, v32
	v_cvt_pk_bf16_f32 v32, v30, v31
	v_cvt_pk_bf16_f32 v33, v41, v33
	v_lshl_add_u64 v[30:31], v[36:37], 0, v[0:1]
	global_store_dwordx2 v[30:31], v[32:33], off
	v_or_b32_e32 v32, 32, v0
	v_mov_b32_e32 v33, v1
	v_lshl_add_u64 v[32:33], v[34:35], 0, v[32:33]
	global_load_dwordx2 v[32:33], v[32:33], off
	s_waitcnt vmcnt(0)
	v_lshlrev_b32_e32 v36, 16, v32
	global_load_dwordx4 v[42:45], v38, s[10:11] offset:64
	v_mul_f32_e32 v39, 0xbfb8aa3b, v36
	v_exp_f32_e32 v39, v39
	v_and_b32_e32 v32, 0xffff0000, v32
	v_lshlrev_b32_e32 v37, 16, v33
	v_and_b32_e32 v33, 0xffff0000, v33
	v_add_f32_e32 v39, 1.0, v39
	v_div_scale_f32 v41, s[0:1], v39, v39, 1.0
	s_waitcnt vmcnt(0)
; DI unsigned pack2(float lo, float hi) { unsigned r; asm("v_cvt_pk_bf16_f32 %0, %1, %2" : "=v"(r) : "v"(lo), "v"(hi)); return r; }
; DI float lo2f(unsigned u) { return __uint_as_float(u << 16); }
; DI float hi2f(unsigned u) { return __uint_as_float(u & 0xffff0000u); }
; DI float sigmoidf_(float x) { return 1.f / (1.f + __expf(-x)); }
; DI void gla_pass3(int item, const bf16_t* __restrict__ z, const float* __restrict__ w_up, const float* __restrict__ b_alpha,
;                   const float* __restrict__ Sbuf, const float* __restrict__ gw, bf16_t* __restrict__ mix, char* smem) {
;     ...
;     for (int dt = 0; dt < 8; ++dt) {
;       const int dv = dt * 16 + 4 * g, col = h * 128 + dv;
;       const u32x2 gq = *(const u32x2*)(z + (tok0 + iq) * ABP + ZG + col);
;       const float gg[4] = {lo2f(gq[0]), hi2f(gq[0]), lo2f(gq[1]), hi2f(gq[1])};
;       const f32x4 w = *(const f32x4*)(gw + dv);
;       float y[4];
; #pragma unroll
;       for (int e = 0; e < 4; ++e) y[e] = o[0][dt][e] * r * w[e] * (gg[e] * sigmoidf_(gg[e]));
;       u32x2 ov; ov[0] = pack2(y[0], y[1]); ov[1] = pack2(y[2], y[3]);
;       *(u32x2*)(mix + (tok0 + iq) * DM + col) = ov;
;     }
	v_mul_f32_e32 v26, v42, v26
	v_rcp_f32_e32 v42, v41
	v_mul_f32_e32 v27, v43, v27
	v_mul_f32_e32 v28, v44, v28
	v_mul_f32_e32 v29, v45, v29
	v_fma_f32 v46, -v41, v42, 1.0
	v_fmac_f32_e32 v42, v46, v42
	v_div_scale_f32 v46, vcc, 1.0, v39, 1.0
	v_mul_f32_e32 v47, v46, v42
	v_fma_f32 v48, -v41, v47, v46
	v_fmac_f32_e32 v47, v48, v42
	v_fma_f32 v41, -v41, v47, v46
	v_div_fmas_f32 v41, v41, v42, v47
	v_div_fixup_f32 v39, v41, v39, 1.0
	v_mul_f32_e32 v36, v39, v36
	v_mul_f32_e32 v26, v26, v36
	v_mul_f32_e32 v36, 0xbfb8aa3b, v32
	v_exp_f32_e32 v36, v36
	s_nop 0
	v_add_f32_e32 v36, 1.0, v36
	v_div_scale_f32 v39, s[0:1], v36, v36, 1.0
	v_rcp_f32_e32 v41, v39
	s_nop 0
	v_fma_f32 v42, -v39, v41, 1.0
	v_fmac_f32_e32 v41, v42, v41
	v_div_scale_f32 v42, vcc, 1.0, v36, 1.0
	v_mul_f32_e32 v43, v42, v41
	v_fma_f32 v46, -v39, v43, v42
	v_fmac_f32_e32 v43, v46, v41
	v_fma_f32 v39, -v39, v43, v42
	v_div_fmas_f32 v39, v39, v41, v43
	v_div_fixup_f32 v36, v39, v36, 1.0
	v_mul_f32_e32 v32, v36, v32
	v_mul_f32_e32 v27, v27, v32
	v_mul_f32_e32 v32, 0xbfb8aa3b, v37
	v_exp_f32_e32 v32, v32
	v_cvt_pk_bf16_f32 v26, v26, v27
	s_nop 0
	v_add_f32_e32 v32, 1.0, v32
	v_div_scale_f32 v36, s[0:1], v32, v32, 1.0
	v_rcp_f32_e32 v39, v36
	s_nop 0
	v_fma_f32 v41, -v36, v39, 1.0
	v_fmac_f32_e32 v39, v41, v39
	v_div_scale_f32 v41, vcc, 1.0, v32, 1.0
	v_mul_f32_e32 v42, v41, v39
	v_fma_f32 v43, -v36, v42, v41
	v_fmac_f32_e32 v42, v43, v39
	v_fma_f32 v36, -v36, v42, v41
	v_div_fmas_f32 v36, v36, v39, v42
	v_div_fixup_f32 v32, v36, v32, 1.0
	v_mul_f32_e32 v32, v32, v37
	v_mul_f32_e32 v28, v28, v32
	v_mul_f32_e32 v32, 0xbfb8aa3b, v33
	v_exp_f32_e32 v32, v32
	s_nop 0
	v_add_f32_e32 v32, 1.0, v32
	v_div_scale_f32 v36, s[0:1], v32, v32, 1.0
	v_rcp_f32_e32 v37, v36
	s_nop 0
	v_fma_f32 v39, -v36, v37, 1.0
	v_fmac_f32_e32 v37, v39, v37
	v_div_scale_f32 v39, vcc, 1.0, v32, 1.0
	v_mul_f32_e32 v41, v39, v37
	v_fma_f32 v42, -v36, v41, v39
	v_fmac_f32_e32 v41, v42, v37
	v_fma_f32 v36, -v36, v41, v39
	v_div_fmas_f32 v36, v36, v37, v41
	v_div_fixup_f32 v32, v36, v32, 1.0
	v_mul_f32_e32 v32, v32, v33
	v_mul_f32_e32 v29, v29, v32
	v_cvt_pk_bf16_f32 v27, v28, v29
	global_store_dwordx2 v[30:31], v[26:27], off offset:32
	v_or_b32_e32 v26, 64, v0
	v_mov_b32_e32 v27, v1
	v_lshl_add_u64 v[26:27], v[34:35], 0, v[26:27]
	global_load_dwordx2 v[26:27], v[26:27], off
	s_waitcnt vmcnt(0)
	v_lshlrev_b32_e32 v32, 16, v26
	v_and_b32_e32 v33, 0xffff0000, v26
	v_lshlrev_b32_e32 v36, 16, v27
	v_and_b32_e32 v37, 0xffff0000, v27
	global_load_dwordx4 v[26:29], v38, s[10:11] offset:128
	s_waitcnt vmcnt(0)
	v_mul_f32_e32 v22, v22, v26
	v_mul_f32_e32 v26, 0xbfb8aa3b, v32
	v_exp_f32_e32 v26, v26
	v_mul_f32_e32 v23, v23, v27
	v_mul_f32_e32 v24, v24, v28
	v_mul_f32_e32 v25, v25, v29
	v_add_f32_e32 v26, 1.0, v26
	v_div_scale_f32 v39, s[0:1], v26, v26, 1.0
	v_rcp_f32_e32 v41, v39
	s_nop 0
	v_fma_f32 v42, -v39, v41, 1.0
	v_fmac_f32_e32 v41, v42, v41
	v_div_scale_f32 v42, vcc, 1.0, v26, 1.0
	v_mul_f32_e32 v43, v42, v41
	v_fma_f32 v44, -v39, v43, v42
	v_fmac_f32_e32 v43, v44, v41
	v_fma_f32 v39, -v39, v43, v42
	v_div_fmas_f32 v39, v39, v41, v43
	v_div_fixup_f32 v26, v39, v26, 1.0
	v_mul_f32_e32 v26, v26, v32
	v_mul_f32_e32 v22, v22, v26
	v_mul_f32_e32 v26, 0xbfb8aa3b, v33
	v_exp_f32_e32 v26, v26
	s_nop 0
	v_add_f32_e32 v26, 1.0, v26
	v_div_scale_f32 v27, s[0:1], v26, v26, 1.0
	v_rcp_f32_e32 v32, v27
	s_nop 0
	v_fma_f32 v39, -v27, v32, 1.0
	v_fmac_f32_e32 v32, v39, v32
	v_div_scale_f32 v39, vcc, 1.0, v26, 1.0
	v_mul_f32_e32 v41, v39, v32
	v_fma_f32 v42, -v27, v41, v39
	v_fmac_f32_e32 v41, v42, v32
	v_fma_f32 v27, -v27, v41, v39
	v_div_fmas_f32 v27, v27, v32, v41
	v_div_fixup_f32 v26, v27, v26, 1.0
	v_mul_f32_e32 v26, v26, v33
	v_mul_f32_e32 v23, v23, v26
	v_mul_f32_e32 v26, 0xbfb8aa3b, v36
	v_exp_f32_e32 v26, v26
	v_cvt_pk_bf16_f32 v22, v22, v23
	s_nop 0
	v_add_f32_e32 v26, 1.0, v26
	v_div_scale_f32 v27, s[0:1], v26, v26, 1.0
	v_rcp_f32_e32 v28, v27
	s_nop 0
	v_fma_f32 v32, -v27, v28, 1.0
	v_fmac_f32_e32 v28, v32, v28
	v_div_scale_f32 v32, vcc, 1.0, v26, 1.0
	v_mul_f32_e32 v33, v32, v28
	v_fma_f32 v39, -v27, v33, v32
	v_fmac_f32_e32 v33, v39, v28
	v_fma_f32 v27, -v27, v33, v32
	v_div_fmas_f32 v27, v27, v28, v33
	v_div_fixup_f32 v26, v27, v26, 1.0
	v_mul_f32_e32 v26, v26, v36
	v_mul_f32_e32 v24, v24, v26
	v_mul_f32_e32 v26, 0xbfb8aa3b, v37
	v_exp_f32_e32 v26, v26
	s_nop 0
	v_add_f32_e32 v26, 1.0, v26
	v_div_scale_f32 v27, s[0:1], v26, v26, 1.0
	v_rcp_f32_e32 v28, v27
	s_nop 0
	v_fma_f32 v29, -v27, v28, 1.0
	v_fmac_f32_e32 v28, v29, v28
	v_div_scale_f32 v29, vcc, 1.0, v26, 1.0
	v_mul_f32_e32 v32, v29, v28
	v_fma_f32 v33, -v27, v32, v29
	v_fmac_f32_e32 v32, v33, v28
	v_fma_f32 v27, -v27, v32, v29
	v_div_fmas_f32 v27, v27, v28, v32
	v_div_fixup_f32 v26, v27, v26, 1.0
	v_mul_f32_e32 v26, v26, v37
	v_mul_f32_e32 v25, v25, v26
	v_cvt_pk_bf16_f32 v23, v24, v25
	global_store_dwordx2 v[30:31], v[22:23], off offset:64
	v_or_b32_e32 v22, 0x60, v0
	v_mov_b32_e32 v23, v1
	v_lshl_add_u64 v[22:23], v[34:35], 0, v[22:23]
	global_load_dwordx2 v[22:23], v[22:23], off
	s_waitcnt vmcnt(0)
	v_lshlrev_b32_e32 v26, 16, v22
	v_and_b32_e32 v27, 0xffff0000, v22
	v_lshlrev_b32_e32 v28, 16, v23
	v_and_b32_e32 v29, 0xffff0000, v23
	global_load_dwordx4 v[22:25], v38, s[10:11] offset:192
	s_waitcnt vmcnt(0)
; DI unsigned pack2(float lo, float hi) { unsigned r; asm("v_cvt_pk_bf16_f32 %0, %1, %2" : "=v"(r) : "v"(lo), "v"(hi)); return r; }
; DI float lo2f(unsigned u) { return __uint_as_float(u << 16); }
; DI float hi2f(unsigned u) { return __uint_as_float(u & 0xffff0000u); }
; DI float sigmoidf_(float x) { return 1.f / (1.f + __expf(-x)); }
; DI void gla_pass3(int item, const bf16_t* __restrict__ z, const float* __restrict__ w_up, const float* __restrict__ b_alpha,
;                   const float* __restrict__ Sbuf, const float* __restrict__ gw, bf16_t* __restrict__ mix, char* smem) {
;     ...
;     for (int dt = 0; dt < 8; ++dt) {
;       const int dv = dt * 16 + 4 * g, col = h * 128 + dv;
;       const u32x2 gq = *(const u32x2*)(z + (tok0 + iq) * ABP + ZG + col);
;       const float gg[4] = {lo2f(gq[0]), hi2f(gq[0]), lo2f(gq[1]), hi2f(gq[1])};
;       const f32x4 w = *(const f32x4*)(gw + dv);
;       float y[4];
; #pragma unroll
;       for (int e = 0; e < 4; ++e) y[e] = o[0][dt][e] * r * w[e] * (gg[e] * sigmoidf_(gg[e]));
;       u32x2 ov; ov[0] = pack2(y[0], y[1]); ov[1] = pack2(y[2], y[3]);
;       *(u32x2*)(mix + (tok0 + iq) * DM + col) = ov;
;     }
	v_mul_f32_e32 v18, v18, v22
	v_mul_f32_e32 v22, 0xbfb8aa3b, v26
	v_exp_f32_e32 v22, v22
	v_mul_f32_e32 v19, v19, v23
	v_mul_f32_e32 v20, v20, v24
	v_mul_f32_e32 v21, v21, v25
	v_add_f32_e32 v22, 1.0, v22
	v_div_scale_f32 v32, s[0:1], v22, v22, 1.0
	v_rcp_f32_e32 v33, v32
	s_nop 0
	v_fma_f32 v36, -v32, v33, 1.0
	v_fmac_f32_e32 v33, v36, v33
	v_div_scale_f32 v36, vcc, 1.0, v22, 1.0
	v_mul_f32_e32 v37, v36, v33
	v_fma_f32 v39, -v32, v37, v36
	v_fmac_f32_e32 v37, v39, v33
	v_fma_f32 v32, -v32, v37, v36
	v_div_fmas_f32 v32, v32, v33, v37
	v_div_fixup_f32 v22, v32, v22, 1.0
	v_mul_f32_e32 v22, v22, v26
	v_mul_f32_e32 v18, v18, v22
	v_mul_f32_e32 v22, 0xbfb8aa3b, v27
	v_exp_f32_e32 v22, v22
	s_nop 0
	v_add_f32_e32 v22, 1.0, v22
	v_div_scale_f32 v23, s[0:1], v22, v22, 1.0
	v_rcp_f32_e32 v26, v23
	s_nop 0
	v_fma_f32 v32, -v23, v26, 1.0
	v_fmac_f32_e32 v26, v32, v26
	v_div_scale_f32 v32, vcc, 1.0, v22, 1.0
	v_mul_f32_e32 v33, v32, v26
	v_fma_f32 v36, -v23, v33, v32
	v_fmac_f32_e32 v33, v36, v26
	v_fma_f32 v23, -v23, v33, v32
	v_div_fmas_f32 v23, v23, v26, v33
	v_div_fixup_f32 v22, v23, v22, 1.0
	v_mul_f32_e32 v22, v22, v27
	v_mul_f32_e32 v19, v19, v22
	v_mul_f32_e32 v22, 0xbfb8aa3b, v28
	v_exp_f32_e32 v22, v22
	v_cvt_pk_bf16_f32 v18, v18, v19
	s_nop 0
	v_add_f32_e32 v22, 1.0, v22
	v_div_scale_f32 v23, s[0:1], v22, v22, 1.0
	v_rcp_f32_e32 v24, v23
	s_nop 0
	v_fma_f32 v26, -v23, v24, 1.0
	v_fmac_f32_e32 v24, v26, v24
	v_div_scale_f32 v26, vcc, 1.0, v22, 1.0
	v_mul_f32_e32 v27, v26, v24
	v_fma_f32 v32, -v23, v27, v26
	v_fmac_f32_e32 v27, v32, v24
	v_fma_f32 v23, -v23, v27, v26
	v_div_fmas_f32 v23, v23, v24, v27
	v_div_fixup_f32 v22, v23, v22, 1.0
	v_mul_f32_e32 v22, v22, v28
	v_mul_f32_e32 v20, v20, v22
	v_mul_f32_e32 v22, 0xbfb8aa3b, v29
	v_exp_f32_e32 v22, v22
	s_nop 0
	v_add_f32_e32 v22, 1.0, v22
	v_div_scale_f32 v23, s[0:1], v22, v22, 1.0
	v_rcp_f32_e32 v24, v23
	s_nop 0
	v_fma_f32 v25, -v23, v24, 1.0
	v_fmac_f32_e32 v24, v25, v24
	v_div_scale_f32 v25, vcc, 1.0, v22, 1.0
	v_mul_f32_e32 v26, v25, v24
	v_fma_f32 v27, -v23, v26, v25
	v_fmac_f32_e32 v26, v27, v24
	v_fma_f32 v23, -v23, v26, v25
	v_div_fmas_f32 v23, v23, v24, v26
	v_div_fixup_f32 v22, v23, v22, 1.0
	v_mul_f32_e32 v22, v22, v29
	v_mul_f32_e32 v21, v21, v22
	v_cvt_pk_bf16_f32 v19, v20, v21
	global_store_dwordx2 v[30:31], v[18:19], off offset:96
	v_or_b32_e32 v18, 0x80, v0
	v_mov_b32_e32 v19, v1
	v_lshl_add_u64 v[18:19], v[34:35], 0, v[18:19]
	global_load_dwordx2 v[18:19], v[18:19], off
	s_waitcnt vmcnt(0)
	v_lshlrev_b32_e32 v25, 16, v18
	v_and_b32_e32 v24, 0xffff0000, v18
	v_lshlrev_b32_e32 v23, 16, v19
	v_and_b32_e32 v22, 0xffff0000, v19
	global_load_dwordx4 v[18:21], v38, s[10:11] offset:256
	s_waitcnt vmcnt(0)
	v_mul_f32_e32 v14, v14, v18
	v_mul_f32_e32 v18, 0xbfb8aa3b, v25
	v_exp_f32_e32 v18, v18
	v_mul_f32_e32 v15, v15, v19
	v_mul_f32_e32 v16, v16, v20
	v_mul_f32_e32 v17, v17, v21
	v_add_f32_e32 v18, 1.0, v18
	v_div_scale_f32 v26, s[0:1], v18, v18, 1.0
	v_rcp_f32_e32 v27, v26
	s_nop 0
	v_fma_f32 v28, -v26, v27, 1.0
	v_fmac_f32_e32 v27, v28, v27
	v_div_scale_f32 v28, vcc, 1.0, v18, 1.0
	v_mul_f32_e32 v29, v28, v27
	v_fma_f32 v32, -v26, v29, v28
	v_fmac_f32_e32 v29, v32, v27
	v_fma_f32 v26, -v26, v29, v28
	v_div_fmas_f32 v26, v26, v27, v29
	v_div_fixup_f32 v18, v26, v18, 1.0
	v_mul_f32_e32 v18, v18, v25
	v_mul_f32_e32 v14, v14, v18
	v_mul_f32_e32 v18, 0xbfb8aa3b, v24
	v_exp_f32_e32 v18, v18
	s_nop 0
	v_add_f32_e32 v18, 1.0, v18
	v_div_scale_f32 v19, s[0:1], v18, v18, 1.0
	v_rcp_f32_e32 v25, v19
	s_nop 0
	v_fma_f32 v26, -v19, v25, 1.0
	v_fmac_f32_e32 v25, v26, v25
	v_div_scale_f32 v26, vcc, 1.0, v18, 1.0
	v_mul_f32_e32 v27, v26, v25
	v_fma_f32 v28, -v19, v27, v26
	v_fmac_f32_e32 v27, v28, v25
	v_fma_f32 v19, -v19, v27, v26
	v_div_fmas_f32 v19, v19, v25, v27
	v_div_fixup_f32 v18, v19, v18, 1.0
	v_mul_f32_e32 v18, v18, v24
	v_mul_f32_e32 v15, v15, v18
	v_mul_f32_e32 v18, 0xbfb8aa3b, v23
	v_exp_f32_e32 v18, v18
	v_cvt_pk_bf16_f32 v14, v14, v15
	s_nop 0
	v_add_f32_e32 v18, 1.0, v18
	v_div_scale_f32 v19, s[0:1], v18, v18, 1.0
	v_rcp_f32_e32 v20, v19
	s_nop 0
	v_fma_f32 v24, -v19, v20, 1.0
	v_fmac_f32_e32 v20, v24, v20
	v_div_scale_f32 v24, vcc, 1.0, v18, 1.0
	v_mul_f32_e32 v25, v24, v20
	v_fma_f32 v26, -v19, v25, v24
	v_fmac_f32_e32 v25, v26, v20
	v_fma_f32 v19, -v19, v25, v24
	v_div_fmas_f32 v19, v19, v20, v25
	v_div_fixup_f32 v18, v19, v18, 1.0
	v_mul_f32_e32 v18, v18, v23
	v_mul_f32_e32 v16, v16, v18
	v_mul_f32_e32 v18, 0xbfb8aa3b, v22
	v_exp_f32_e32 v18, v18
	s_nop 0
	v_add_f32_e32 v18, 1.0, v18
	v_div_scale_f32 v19, s[0:1], v18, v18, 1.0
	v_rcp_f32_e32 v20, v19
	s_nop 0
	v_fma_f32 v21, -v19, v20, 1.0
	v_fmac_f32_e32 v20, v21, v20
	v_div_scale_f32 v21, vcc, 1.0, v18, 1.0
	v_mul_f32_e32 v23, v21, v20
	v_fma_f32 v24, -v19, v23, v21
	v_fmac_f32_e32 v23, v24, v20
	v_fma_f32 v19, -v19, v23, v21
	v_div_fmas_f32 v19, v19, v20, v23
	v_div_fixup_f32 v18, v19, v18, 1.0
	v_mul_f32_e32 v18, v18, v22
	v_mul_f32_e32 v17, v17, v18
	v_cvt_pk_bf16_f32 v15, v16, v17
	global_store_dwordx2 v[30:31], v[14:15], off offset:128
	v_or_b32_e32 v14, 0xa0, v0
	v_mov_b32_e32 v15, v1
	v_lshl_add_u64 v[14:15], v[34:35], 0, v[14:15]
	global_load_dwordx2 v[14:15], v[14:15], off
	s_waitcnt vmcnt(0)
	v_lshlrev_b32_e32 v18, 16, v14
	v_and_b32_e32 v19, 0xffff0000, v14
	v_lshlrev_b32_e32 v20, 16, v15
	v_and_b32_e32 v21, 0xffff0000, v15
	global_load_dwordx4 v[14:17], v38, s[10:11] offset:320
	s_waitcnt vmcnt(0)
; DI unsigned pack2(float lo, float hi) { unsigned r; asm("v_cvt_pk_bf16_f32 %0, %1, %2" : "=v"(r) : "v"(lo), "v"(hi)); return r; }
; DI float lo2f(unsigned u) { return __uint_as_float(u << 16); }
; DI float hi2f(unsigned u) { return __uint_as_float(u & 0xffff0000u); }
; DI float sigmoidf_(float x) { return 1.f / (1.f + __expf(-x)); }
; DI void gla_pass3(int item, const bf16_t* __restrict__ z, const float* __restrict__ w_up, const float* __restrict__ b_alpha,
;                   const float* __restrict__ Sbuf, const float* __restrict__ gw, bf16_t* __restrict__ mix, char* smem) {
;     ...
;     for (int dt = 0; dt < 8; ++dt) {
;       const int dv = dt * 16 + 4 * g, col = h * 128 + dv;
;       const u32x2 gq = *(const u32x2*)(z + (tok0 + iq) * ABP + ZG + col);
;       const float gg[4] = {lo2f(gq[0]), hi2f(gq[0]), lo2f(gq[1]), hi2f(gq[1])};
;       const f32x4 w = *(const f32x4*)(gw + dv);
;       float y[4];
; #pragma unroll
;       for (int e = 0; e < 4; ++e) y[e] = o[0][dt][e] * r * w[e] * (gg[e] * sigmoidf_(gg[e]));
;       u32x2 ov; ov[0] = pack2(y[0], y[1]); ov[1] = pack2(y[2], y[3]);
;       *(u32x2*)(mix + (tok0 + iq) * DM + col) = ov;
;     }
	v_mul_f32_e32 v10, v10, v14
	v_mul_f32_e32 v14, 0xbfb8aa3b, v18
	v_exp_f32_e32 v14, v14
	v_mul_f32_e32 v11, v11, v15
	v_mul_f32_e32 v12, v12, v16
	v_mul_f32_e32 v13, v13, v17
	v_add_f32_e32 v14, 1.0, v14
	v_div_scale_f32 v22, s[0:1], v14, v14, 1.0
	v_rcp_f32_e32 v23, v22
	s_nop 0
	v_fma_f32 v24, -v22, v23, 1.0
	v_fmac_f32_e32 v23, v24, v23
	v_div_scale_f32 v24, vcc, 1.0, v14, 1.0
	v_mul_f32_e32 v25, v24, v23
	v_fma_f32 v26, -v22, v25, v24
	v_fmac_f32_e32 v25, v26, v23
	v_fma_f32 v22, -v22, v25, v24
	v_div_fmas_f32 v22, v22, v23, v25
	v_div_fixup_f32 v14, v22, v14, 1.0
	v_mul_f32_e32 v14, v14, v18
	v_mul_f32_e32 v10, v10, v14
	v_mul_f32_e32 v14, 0xbfb8aa3b, v19
	v_exp_f32_e32 v14, v14
	s_nop 0
	v_add_f32_e32 v14, 1.0, v14
	v_div_scale_f32 v15, s[0:1], v14, v14, 1.0
	v_rcp_f32_e32 v18, v15
	s_nop 0
	v_fma_f32 v22, -v15, v18, 1.0
	v_fmac_f32_e32 v18, v22, v18
	v_div_scale_f32 v22, vcc, 1.0, v14, 1.0
	v_mul_f32_e32 v23, v22, v18
	v_fma_f32 v24, -v15, v23, v22
	v_fmac_f32_e32 v23, v24, v18
	v_fma_f32 v15, -v15, v23, v22
	v_div_fmas_f32 v15, v15, v18, v23
	v_div_fixup_f32 v14, v15, v14, 1.0
	v_mul_f32_e32 v14, v14, v19
	v_mul_f32_e32 v11, v11, v14
	v_mul_f32_e32 v14, 0xbfb8aa3b, v20
	v_exp_f32_e32 v14, v14
	v_cvt_pk_bf16_f32 v10, v10, v11
	s_nop 0
	v_add_f32_e32 v14, 1.0, v14
	v_div_scale_f32 v15, s[0:1], v14, v14, 1.0
	v_rcp_f32_e32 v16, v15
	s_nop 0
	v_fma_f32 v18, -v15, v16, 1.0
	v_fmac_f32_e32 v16, v18, v16
	v_div_scale_f32 v18, vcc, 1.0, v14, 1.0
	v_mul_f32_e32 v19, v18, v16
	v_fma_f32 v22, -v15, v19, v18
	v_fmac_f32_e32 v19, v22, v16
	v_fma_f32 v15, -v15, v19, v18
	v_div_fmas_f32 v15, v15, v16, v19
	v_div_fixup_f32 v14, v15, v14, 1.0
	v_mul_f32_e32 v14, v14, v20
	v_mul_f32_e32 v12, v12, v14
	v_mul_f32_e32 v14, 0xbfb8aa3b, v21
	v_exp_f32_e32 v14, v14
	s_nop 0
	v_add_f32_e32 v14, 1.0, v14
	v_div_scale_f32 v15, s[0:1], v14, v14, 1.0
	v_rcp_f32_e32 v16, v15
	s_nop 0
	v_fma_f32 v17, -v15, v16, 1.0
	v_fmac_f32_e32 v16, v17, v16
	v_div_scale_f32 v17, vcc, 1.0, v14, 1.0
	v_mul_f32_e32 v18, v17, v16
	v_fma_f32 v19, -v15, v18, v17
	v_fmac_f32_e32 v18, v19, v16
	v_fma_f32 v15, -v15, v18, v17
	v_div_fmas_f32 v15, v15, v16, v18
	v_div_fixup_f32 v14, v15, v14, 1.0
	v_mul_f32_e32 v14, v14, v21
	v_mul_f32_e32 v13, v13, v14
	v_cvt_pk_bf16_f32 v11, v12, v13
	global_store_dwordx2 v[30:31], v[10:11], off offset:160
	v_or_b32_e32 v10, 0xc0, v0
	v_mov_b32_e32 v11, v1
	v_lshl_add_u64 v[10:11], v[34:35], 0, v[10:11]
	global_load_dwordx2 v[10:11], v[10:11], off
	v_or_b32_e32 v0, 0xe0, v0
	s_waitcnt vmcnt(0)
	v_lshlrev_b32_e32 v14, 16, v10
	v_and_b32_e32 v15, 0xffff0000, v10
	v_lshlrev_b32_e32 v16, 16, v11
	v_and_b32_e32 v17, 0xffff0000, v11
	global_load_dwordx4 v[10:13], v38, s[10:11] offset:384
	s_waitcnt vmcnt(0)
; DI unsigned pack2(float lo, float hi) { unsigned r; asm("v_cvt_pk_bf16_f32 %0, %1, %2" : "=v"(r) : "v"(lo), "v"(hi)); return r; }
; DI float lo2f(unsigned u) { return __uint_as_float(u << 16); }
; DI float hi2f(unsigned u) { return __uint_as_float(u & 0xffff0000u); }
; DI float sigmoidf_(float x) { return 1.f / (1.f + __expf(-x)); }
; DI void gla_pass3(int item, const bf16_t* __restrict__ z, const float* __restrict__ w_up, const float* __restrict__ b_alpha,
;                   const float* __restrict__ Sbuf, const float* __restrict__ gw, bf16_t* __restrict__ mix, char* smem) {
;     ...
;     for (int dt = 0; dt < 8; ++dt) {
;       const int dv = dt * 16 + 4 * g, col = h * 128 + dv;
;       const u32x2 gq = *(const u32x2*)(z + (tok0 + iq) * ABP + ZG + col);
;       const float gg[4] = {lo2f(gq[0]), hi2f(gq[0]), lo2f(gq[1]), hi2f(gq[1])};
;       const f32x4 w = *(const f32x4*)(gw + dv);
;       float y[4];
; #pragma unroll
;       for (int e = 0; e < 4; ++e) y[e] = o[0][dt][e] * r * w[e] * (gg[e] * sigmoidf_(gg[e]));
;       u32x2 ov; ov[0] = pack2(y[0], y[1]); ov[1] = pack2(y[2], y[3]);
;       *(u32x2*)(mix + (tok0 + iq) * DM + col) = ov;
;     }
; __global__ void __launch_bounds__(256, 2) mega(Params p) {
;     ...
;       for (int it = blockIdx.x; it < 1024; it += gridDim.x) gla_pass3(it, zb, p.in[8] + (size_t)j * 16 * 512, p.in[9] + (size_t)j * 512, Ubuf, p.in[10] + j * 128, mix, smem);
	v_mul_f32_e32 v6, v6, v10
	v_mul_f32_e32 v10, 0xbfb8aa3b, v14
	v_exp_f32_e32 v10, v10
	v_mul_f32_e32 v7, v7, v11
	v_mul_f32_e32 v8, v8, v12
	v_mul_f32_e32 v9, v9, v13
	v_add_f32_e32 v10, 1.0, v10
	v_div_scale_f32 v18, s[0:1], v10, v10, 1.0
	v_rcp_f32_e32 v19, v18
	s_nop 0
	v_fma_f32 v20, -v18, v19, 1.0
	v_fmac_f32_e32 v19, v20, v19
	v_div_scale_f32 v20, vcc, 1.0, v10, 1.0
	v_mul_f32_e32 v21, v20, v19
	v_fma_f32 v22, -v18, v21, v20
	v_fmac_f32_e32 v21, v22, v19
	v_fma_f32 v18, -v18, v21, v20
	v_div_fmas_f32 v18, v18, v19, v21
	v_div_fixup_f32 v10, v18, v10, 1.0
	v_mul_f32_e32 v10, v10, v14
	v_mul_f32_e32 v6, v6, v10
	v_mul_f32_e32 v10, 0xbfb8aa3b, v15
	v_exp_f32_e32 v10, v10
	s_nop 0
	v_add_f32_e32 v10, 1.0, v10
	v_div_scale_f32 v11, s[0:1], v10, v10, 1.0
	v_rcp_f32_e32 v14, v11
	s_nop 0
	v_fma_f32 v18, -v11, v14, 1.0
	v_fmac_f32_e32 v14, v18, v14
	v_div_scale_f32 v18, vcc, 1.0, v10, 1.0
	v_mul_f32_e32 v19, v18, v14
	v_fma_f32 v20, -v11, v19, v18
	v_fmac_f32_e32 v19, v20, v14
	v_fma_f32 v11, -v11, v19, v18
	v_div_fmas_f32 v11, v11, v14, v19
	v_div_fixup_f32 v10, v11, v10, 1.0
	v_mul_f32_e32 v10, v10, v15
	v_mul_f32_e32 v7, v7, v10
	v_mul_f32_e32 v10, 0xbfb8aa3b, v16
	v_exp_f32_e32 v10, v10
	v_cvt_pk_bf16_f32 v6, v6, v7
	s_nop 0
	v_add_f32_e32 v10, 1.0, v10
	v_div_scale_f32 v11, s[0:1], v10, v10, 1.0
	v_rcp_f32_e32 v12, v11
	s_nop 0
	v_fma_f32 v14, -v11, v12, 1.0
	v_fmac_f32_e32 v12, v14, v12
	v_div_scale_f32 v14, vcc, 1.0, v10, 1.0
	v_mul_f32_e32 v15, v14, v12
	v_fma_f32 v18, -v11, v15, v14
	v_fmac_f32_e32 v15, v18, v12
	v_fma_f32 v11, -v11, v15, v14
	v_div_fmas_f32 v11, v11, v12, v15
	v_div_fixup_f32 v10, v11, v10, 1.0
	v_mul_f32_e32 v10, v10, v16
	v_mul_f32_e32 v8, v8, v10
	v_mul_f32_e32 v10, 0xbfb8aa3b, v17
	v_exp_f32_e32 v10, v10
	s_nop 0
	v_add_f32_e32 v10, 1.0, v10
	v_div_scale_f32 v11, s[0:1], v10, v10, 1.0
	v_rcp_f32_e32 v12, v11
	s_nop 0
	v_fma_f32 v13, -v11, v12, 1.0
	v_fmac_f32_e32 v12, v13, v12
	v_div_scale_f32 v13, vcc, 1.0, v10, 1.0
	v_mul_f32_e32 v14, v13, v12
	v_fma_f32 v15, -v11, v14, v13
	v_fmac_f32_e32 v14, v15, v12
	v_fma_f32 v11, -v11, v14, v13
	v_div_fmas_f32 v11, v11, v12, v14
	v_div_fixup_f32 v10, v11, v10, 1.0
	v_mul_f32_e32 v10, v10, v17
	v_mul_f32_e32 v9, v9, v10
	v_cvt_pk_bf16_f32 v7, v8, v9
	global_store_dwordx2 v[30:31], v[6:7], off offset:192
	v_lshl_add_u64 v[6:7], v[34:35], 0, v[0:1]
	global_load_dwordx2 v[6:7], v[6:7], off
	s_waitcnt vmcnt(0)
	v_lshlrev_b32_e32 v12, 16, v6
	v_and_b32_e32 v11, 0xffff0000, v6
	v_lshlrev_b32_e32 v10, 16, v7
	v_and_b32_e32 v0, 0xffff0000, v7
	global_load_dwordx4 v[6:9], v38, s[10:11] offset:448
	s_waitcnt vmcnt(0)
	v_mul_f32_e32 v2, v2, v6
	v_mul_f32_e32 v6, 0xbfb8aa3b, v12
	v_exp_f32_e32 v6, v6
	v_mul_f32_e32 v3, v3, v7
	v_mul_f32_e32 v4, v4, v8
	v_mul_f32_e32 v5, v5, v9
	v_add_f32_e32 v6, 1.0, v6
	v_div_scale_f32 v13, s[0:1], v6, v6, 1.0
	v_rcp_f32_e32 v14, v13
	s_nop 0
	v_fma_f32 v15, -v13, v14, 1.0
	v_fmac_f32_e32 v14, v15, v14
	v_div_scale_f32 v15, vcc, 1.0, v6, 1.0
	v_mul_f32_e32 v16, v15, v14
	v_fma_f32 v17, -v13, v16, v15
	v_fmac_f32_e32 v16, v17, v14
	v_fma_f32 v13, -v13, v16, v15
	v_div_fmas_f32 v13, v13, v14, v16
	v_div_fixup_f32 v6, v13, v6, 1.0
	v_mul_f32_e32 v6, v6, v12
	v_mul_f32_e32 v2, v2, v6
	v_mul_f32_e32 v6, 0xbfb8aa3b, v11
	v_exp_f32_e32 v6, v6
	s_nop 0
	v_add_f32_e32 v6, 1.0, v6
	v_div_scale_f32 v7, s[0:1], v6, v6, 1.0
	v_rcp_f32_e32 v12, v7
	s_nop 0
	v_fma_f32 v13, -v7, v12, 1.0
	v_fmac_f32_e32 v12, v13, v12
	v_div_scale_f32 v13, vcc, 1.0, v6, 1.0
	v_mul_f32_e32 v14, v13, v12
	v_fma_f32 v15, -v7, v14, v13
	v_fmac_f32_e32 v14, v15, v12
	v_fma_f32 v7, -v7, v14, v13
	v_div_fmas_f32 v7, v7, v12, v14
	v_div_fixup_f32 v6, v7, v6, 1.0
	v_mul_f32_e32 v6, v6, v11
	v_mul_f32_e32 v3, v3, v6
	v_mul_f32_e32 v6, 0xbfb8aa3b, v10
	v_exp_f32_e32 v6, v6
	v_cvt_pk_bf16_f32 v2, v2, v3
	s_nop 0
	v_add_f32_e32 v6, 1.0, v6
	v_div_scale_f32 v7, s[0:1], v6, v6, 1.0
	v_rcp_f32_e32 v8, v7
	s_nop 0
	v_fma_f32 v11, -v7, v8, 1.0
	v_fmac_f32_e32 v8, v11, v8
	v_div_scale_f32 v11, vcc, 1.0, v6, 1.0
	v_mul_f32_e32 v12, v11, v8
	v_fma_f32 v13, -v7, v12, v11
	v_fmac_f32_e32 v12, v13, v8
	v_fma_f32 v7, -v7, v12, v11
	v_div_fmas_f32 v7, v7, v8, v12
	v_div_fixup_f32 v6, v7, v6, 1.0
	v_mul_f32_e32 v6, v6, v10
	v_mul_f32_e32 v4, v4, v6
	v_mul_f32_e32 v6, 0xbfb8aa3b, v0
	v_exp_f32_e32 v6, v6
	s_nop 0
	v_add_f32_e32 v6, 1.0, v6
	v_div_scale_f32 v7, s[0:1], v6, v6, 1.0
	v_rcp_f32_e32 v8, v7
	v_readlane_b32 s0, v253, 52
	s_add_i32 s12, s12, 32
	s_cmp_ge_i32 s12, s101
	v_fma_f32 v9, -v7, v8, 1.0
	v_fmac_f32_e32 v8, v9, v8
	v_div_scale_f32 v9, vcc, 1.0, v6, 1.0
	v_mul_f32_e32 v10, v9, v8
	v_fma_f32 v11, -v7, v10, v9
	v_fmac_f32_e32 v10, v11, v8
	v_fma_f32 v7, -v7, v10, v9
	v_div_fmas_f32 v7, v7, v8, v10
	v_div_fixup_f32 v6, v7, v6, 1.0
	v_mul_f32_e32 v0, v6, v0
	v_mul_f32_e32 v0, v5, v0
	v_cvt_pk_bf16_f32 v3, v4, v0
	global_store_dwordx2 v[30:31], v[2:3], off offset:224
	v_readlane_b32 s1, v253, 53
	s_cbranch_scc1 .LBB0_960
